# adaLN GEMV weight rows prefetched four 4-row steps ahead (loop unrolled by 4)
# speedup vs baseline: 1.0017x; 1.0005x over previous
; DI void phase_prep(const Params& P, char* smem) {
;     ...
;       const int nl = tid & 63, ks = tid >> 6;
;       float acc[17];
; #pragma unroll
;       for (int r = 0; r < 17; ++r) acc[r] = 0.f;
;       const float* wp = P.w_mod + ((size_t)layer * 1024 + ks * 128) * 3072 + n0 + nl;
;       for (int k = 0; k < 128; ++k) {
;         const float wv = wp[(size_t)k * 3072];
; #pragma unroll
;         for (int r = 0; r < 17; ++r) acc[r] += s[r * 1024 + ks * 128 + k] * wv;
;       }
.LBB0_839:
	s_or_b64 exec, exec, s[0:1]
	s_mul_hi_i32 s0, s74, 0x2aaaaaab
	s_lshr_b32 s1, s0, 31
	s_ashr_i32 s44, s0, 3
	s_add_i32 s44, s44, s1
	s_mul_i32 s0, s44, 48
	s_sub_i32 s0, s74, s0
	s_lshl_b32 s0, s0, 6
	s_ashr_i32 s1, s0, 31
	s_mul_i32 s25, s44, 0xc00000
	s_lshl_b64 s[2:3], s[0:1], 2
	s_mul_hi_i32 s24, s44, 0xc00000
	s_add_u32 s2, s25, s2
	s_addc_u32 s3, s24, s3
	v_mov_b32_e32 v60, 0
	v_lshl_add_u64 v[42:43], v[40:41], 0, s[2:3]
	s_mov_b32 s1, 0
	v_mov_b32_e32 v61, v60
	v_mov_b32_e32 v64, v60
	v_mov_b32_e32 v65, v60
	v_mov_b32_e32 v66, v60
	v_mov_b32_e32 v67, v60
	v_mov_b32_e32 v68, v60
	v_mov_b32_e32 v69, v60
	v_mov_b32_e32 v70, v60
	v_mov_b32_e32 v71, v60
	v_mov_b32_e32 v72, v60
	v_mov_b32_e32 v73, v60
	v_mov_b32_e32 v74, v60
	v_mov_b32_e32 v75, v60
	v_mov_b32_e32 v76, v60
	v_mov_b32_e32 v77, v60
	v_mov_b32_e32 v86, v60
	s_waitcnt vmcnt(0) lgkmcnt(0)
	s_barrier
	s_mov_b32 s2, 0xffff7000
	v_add_co_u32_e32 v130, vcc, s2, v42
	s_nop 1
	v_addc_co_u32_e32 v131, vcc, -1, v43, vcc
	global_load_dword v104, v[130:131], off
	s_mov_b32 s2, 0xffffa000
	v_add_co_u32_e32 v130, vcc, s2, v42
	s_nop 1
	v_addc_co_u32_e32 v131, vcc, -1, v43, vcc
	global_load_dword v105, v[130:131], off
	s_mov_b32 s2, 0xffffd000
	v_add_co_u32_e32 v130, vcc, s2, v42
	s_nop 1
	v_addc_co_u32_e32 v131, vcc, -1, v43, vcc
	global_load_dword v106, v[130:131], off
	v_mov_b64_e32 v[130:131], v[42:43]
	global_load_dword v107, v[130:131], off
	s_mov_b64 s[2:3], 0x3000
	v_lshl_add_u64 v[130:131], v[42:43], 0, s[2:3]
	global_load_dword v108, v[130:131], off
	s_mov_b64 s[2:3], 0x6000
	v_lshl_add_u64 v[130:131], v[42:43], 0, s[2:3]
	global_load_dword v109, v[130:131], off
	s_mov_b64 s[2:3], 0x9000
	v_lshl_add_u64 v[130:131], v[42:43], 0, s[2:3]
	global_load_dword v110, v[130:131], off
	s_mov_b64 s[2:3], 0xc000
	v_lshl_add_u64 v[130:131], v[42:43], 0, s[2:3]
	global_load_dword v111, v[130:131], off
	s_mov_b64 s[2:3], 0xf000
	v_lshl_add_u64 v[130:131], v[42:43], 0, s[2:3]
	global_load_dword v112, v[130:131], off
	s_mov_b64 s[2:3], 0x12000
	v_lshl_add_u64 v[130:131], v[42:43], 0, s[2:3]
	global_load_dword v113, v[130:131], off
	s_mov_b64 s[2:3], 0x15000
	v_lshl_add_u64 v[130:131], v[42:43], 0, s[2:3]
	global_load_dword v114, v[130:131], off
	s_mov_b64 s[2:3], 0x18000
	v_lshl_add_u64 v[130:131], v[42:43], 0, s[2:3]
	global_load_dword v115, v[130:131], off
	s_mov_b64 s[2:3], 0x1b000
	v_lshl_add_u64 v[130:131], v[42:43], 0, s[2:3]
	global_load_dword v116, v[130:131], off
	s_mov_b64 s[2:3], 0x1e000
	v_lshl_add_u64 v[130:131], v[42:43], 0, s[2:3]
	global_load_dword v117, v[130:131], off
	s_mov_b64 s[2:3], 0x21000
	v_lshl_add_u64 v[130:131], v[42:43], 0, s[2:3]
	global_load_dword v118, v[130:131], off
	s_mov_b64 s[2:3], 0x24000
	v_lshl_add_u64 v[130:131], v[42:43], 0, s[2:3]
	global_load_dword v119, v[130:131], off
.LBB0_840:
	s_cmp_lt_u32 s1, 0x1c0
	s_cbranch_scc0 .Lprep4_t0
	s_waitcnt vmcnt(12)
	s_branch .Lprep4_w0

; DI void phase_prep(const Params& P, char* smem) {
;     ...
;       for (int k = 0; k < 128; ++k) {
;         const float wv = wp[(size_t)k * 3072];
; #pragma unroll
;         for (int r = 0; r < 17; ++r) acc[r] += s[r * 1024 + ks * 128 + k] * wv;
;       }
.Lprep4_w0:
	v_mov_b32_e32 v120, v104
	v_mov_b32_e32 v122, v105
	v_mov_b32_e32 v124, v106
	v_mov_b32_e32 v126, v107
	s_cmp_lt_u32 s1, 0x1c0
	s_cbranch_scc0 .Lprep4_n0
	s_mov_b64 s[2:3], 0x27000
	v_lshl_add_u64 v[130:131], v[42:43], 0, s[2:3]
	global_load_dword v104, v[130:131], off
	s_mov_b64 s[2:3], 0x2a000
	v_lshl_add_u64 v[130:131], v[42:43], 0, s[2:3]
	global_load_dword v105, v[130:131], off
	s_mov_b64 s[2:3], 0x2d000
	v_lshl_add_u64 v[130:131], v[42:43], 0, s[2:3]
	global_load_dword v106, v[130:131], off
	s_mov_b64 s[2:3], 0x30000
	v_lshl_add_u64 v[130:131], v[42:43], 0, s[2:3]
	global_load_dword v107, v[130:131], off
.Lprep4_n0:
	v_add_u32_e32 v87, s1, v81
	ds_read_b128 v[20:23], v87
	ds_read_b128 v[0:3], v87 offset:4096
	ds_read_b128 v[24:27], v87 offset:8192
	ds_read_b128 v[4:7], v87 offset:12288
	ds_read_b128 v[28:31], v87 offset:16384
	ds_read_b128 v[8:11], v87 offset:20480
	ds_read_b128 v[32:35], v87 offset:24576
	ds_read_b128 v[12:15], v87 offset:28672
	ds_read_b128 v[44:47], v87 offset:32768
	ds_read_b128 v[16:19], v87 offset:36864
	s_waitcnt lgkmcnt(9)
	v_mov_b32_e32 v62, v20
	s_waitcnt lgkmcnt(8)
	v_mov_b32_e32 v63, v0
	s_waitcnt lgkmcnt(7)
	v_mov_b32_e32 v88, v24
	s_waitcnt lgkmcnt(6)
	v_mov_b32_e32 v89, v4
	v_mov_b32_e32 v0, v21
	v_mov_b32_e32 v52, v22
	v_mov_b32_e32 v53, v2
	v_mov_b32_e32 v2, v23
	v_mov_b32_e32 v4, v25
	v_mov_b32_e32 v54, v26
	v_mov_b32_e32 v55, v6
	v_mov_b32_e32 v6, v27
	ds_read_b128 v[24:27], v87 offset:40960
	ds_read_b128 v[20:23], v87 offset:45056
	s_waitcnt lgkmcnt(7)
	v_mov_b32_e32 v90, v28
	s_waitcnt lgkmcnt(6)
	v_mov_b32_e32 v91, v8
	v_mov_b32_e32 v8, v29
	v_mov_b32_e32 v56, v30
	v_mov_b32_e32 v57, v10
	v_mov_b32_e32 v10, v31
	s_waitcnt lgkmcnt(3)
	v_mov_b32_e32 v94, v44
	s_waitcnt lgkmcnt(2)
	v_mov_b32_e32 v95, v16
	v_mov_b32_e32 v16, v45
	v_mov_b32_e32 v44, v46
	v_mov_b32_e32 v45, v18
	v_mov_b32_e32 v18, v47
	s_waitcnt lgkmcnt(1)
	v_mov_b32_e32 v96, v24
	s_waitcnt lgkmcnt(0)
	v_mov_b32_e32 v97, v20
	v_mov_b32_e32 v20, v25
	v_mov_b32_e32 v46, v26
	v_mov_b32_e32 v47, v22
	v_mov_b32_e32 v22, v27
	ds_read_b128 v[28:31], v87 offset:49152
	ds_read_b128 v[24:27], v87 offset:53248
	v_mov_b32_e32 v92, v32
	v_mov_b32_e32 v93, v12
	v_mov_b32_e32 v12, v33
	v_mov_b32_e32 v58, v34
	v_mov_b32_e32 v59, v14
	v_mov_b32_e32 v14, v35
	s_waitcnt lgkmcnt(1)
	v_mov_b32_e32 v98, v28
	s_waitcnt lgkmcnt(0)
	v_mov_b32_e32 v99, v24
	v_mov_b32_e32 v24, v29
	v_mov_b32_e32 v48, v30
	v_mov_b32_e32 v49, v26
	v_mov_b32_e32 v26, v31
	ds_read_b128 v[32:35], v87 offset:57344
	ds_read_b128 v[28:31], v87 offset:61440
	s_mov_b32 s2, 0xffff7000
	s_add_i32 s1, s1, 16
	s_cmpk_eq_i32 s1, 0x200
	s_waitcnt lgkmcnt(1)
	v_mov_b32_e32 v100, v32
	v_add_co_u32_e32 v32, vcc, s2, v42
	s_waitcnt lgkmcnt(0)
	v_mov_b32_e32 v101, v28
	v_mov_b32_e32 v28, v33
	v_addc_co_u32_e32 v33, vcc, -1, v43, vcc
	v_mov_b32_e32 v102, v120
	v_add_u32_e32 v32, 0x10000, v87
	v_mov_b32_e32 v50, v34
	v_mov_b32_e32 v51, v30
	v_mov_b32_e32 v30, v35
	ds_read_b128 v[32:35], v32
	s_movk_i32 s2, 0xa000
	v_pk_fma_f32 v[62:63], v[102:103], v[62:63], v[60:61] op_sel_hi:[0,1,1]
	v_add_co_u32_e32 v60, vcc, s2, v42
	s_movk_i32 s2, 0xd000
	s_nop 0
	v_addc_co_u32_e32 v61, vcc, -1, v43, vcc
	v_pk_fma_f32 v[64:65], v[102:103], v[88:89], v[64:65] op_sel_hi:[0,1,1]
	v_add_co_u32_e32 v88, vcc, s2, v42
	v_pk_fma_f32 v[66:67], v[102:103], v[90:91], v[66:67] op_sel_hi:[0,1,1]
	s_waitcnt lgkmcnt(0)
	v_fmac_f32_e32 v86, v102, v32
	v_addc_co_u32_e32 v89, vcc, -1, v43, vcc
	v_mov_b32_e32 v90, v122
	s_nop 0
	v_mov_b32_e32 v60, v124
	v_mov_b32_e32 v32, v126
	v_pk_fma_f32 v[68:69], v[102:103], v[92:93], v[68:69] op_sel_hi:[0,1,1]
	v_pk_fma_f32 v[70:71], v[102:103], v[94:95], v[70:71] op_sel_hi:[0,1,1]
	v_pk_fma_f32 v[72:73], v[102:103], v[96:97], v[72:73] op_sel_hi:[0,1,1]
	v_pk_fma_f32 v[74:75], v[102:103], v[98:99], v[74:75] op_sel_hi:[0,1,1]
	v_pk_fma_f32 v[76:77], v[102:103], v[100:101], v[76:77] op_sel_hi:[0,1,1]
	s_mov_b64 s[2:3], 0xc000
	v_lshl_add_u64 v[42:43], v[42:43], 0, s[2:3]
	v_pk_fma_f32 v[62:63], v[90:91], v[0:1], v[62:63] op_sel_hi:[0,1,1]
	v_pk_fma_f32 v[64:65], v[90:91], v[4:5], v[64:65] op_sel_hi:[0,1,1]
	v_pk_fma_f32 v[66:67], v[90:91], v[8:9], v[66:67] op_sel_hi:[0,1,1]
	v_pk_fma_f32 v[68:69], v[90:91], v[12:13], v[68:69] op_sel_hi:[0,1,1]
	v_pk_fma_f32 v[0:1], v[90:91], v[16:17], v[70:71] op_sel_hi:[0,1,1]
	v_pk_fma_f32 v[4:5], v[90:91], v[20:21], v[72:73] op_sel_hi:[0,1,1]
	v_pk_fma_f32 v[8:9], v[90:91], v[24:25], v[74:75] op_sel_hi:[0,1,1]
	v_pk_fma_f32 v[12:13], v[90:91], v[28:29], v[76:77] op_sel_hi:[0,1,1]
	v_fmac_f32_e32 v86, v90, v33
	v_pk_fma_f32 v[16:17], v[60:61], v[52:53], v[62:63] op_sel_hi:[0,1,1]
	v_pk_fma_f32 v[20:21], v[60:61], v[54:55], v[64:65] op_sel_hi:[0,1,1]
	v_pk_fma_f32 v[24:25], v[60:61], v[56:57], v[66:67] op_sel_hi:[0,1,1]
	v_pk_fma_f32 v[28:29], v[60:61], v[58:59], v[68:69] op_sel_hi:[0,1,1]
	v_pk_fma_f32 v[0:1], v[60:61], v[44:45], v[0:1] op_sel_hi:[0,1,1]
	v_pk_fma_f32 v[4:5], v[60:61], v[46:47], v[4:5] op_sel_hi:[0,1,1]
	v_pk_fma_f32 v[8:9], v[60:61], v[48:49], v[8:9] op_sel_hi:[0,1,1]
	v_pk_fma_f32 v[12:13], v[60:61], v[50:51], v[12:13] op_sel_hi:[0,1,1]
	v_fmac_f32_e32 v86, v60, v34
	v_pk_fma_f32 v[60:61], v[32:33], v[2:3], v[16:17] op_sel_hi:[0,1,1]
	v_pk_fma_f32 v[64:65], v[32:33], v[6:7], v[20:21] op_sel_hi:[0,1,1]
	v_pk_fma_f32 v[66:67], v[32:33], v[10:11], v[24:25] op_sel_hi:[0,1,1]
	v_pk_fma_f32 v[68:69], v[32:33], v[14:15], v[28:29] op_sel_hi:[0,1,1]
	v_pk_fma_f32 v[70:71], v[32:33], v[18:19], v[0:1] op_sel_hi:[0,1,1]
	v_pk_fma_f32 v[72:73], v[32:33], v[22:23], v[4:5] op_sel_hi:[0,1,1]
	v_pk_fma_f32 v[74:75], v[32:33], v[26:27], v[8:9] op_sel_hi:[0,1,1]
	v_pk_fma_f32 v[76:77], v[32:33], v[30:31], v[12:13] op_sel_hi:[0,1,1]
	v_fmac_f32_e32 v86, v32, v35
	s_cmp_lt_u32 s1, 0x1c0
	s_cbranch_scc0 .Lprep4_t1
	s_waitcnt vmcnt(12)
	s_branch .Lprep4_w1

; DI void phase_prep(const Params& P, char* smem) {
;     ...
;       for (int k = 0; k < 128; ++k) {
;         const float wv = wp[(size_t)k * 3072];
; #pragma unroll
;         for (int r = 0; r < 17; ++r) acc[r] += s[r * 1024 + ks * 128 + k] * wv;
;       }
.Lprep4_w1:
	v_mov_b32_e32 v120, v108
	v_mov_b32_e32 v122, v109
	v_mov_b32_e32 v124, v110
	v_mov_b32_e32 v126, v111
	s_cmp_lt_u32 s1, 0x1c0
	s_cbranch_scc0 .Lprep4_n1
	s_mov_b64 s[2:3], 0x27000
	v_lshl_add_u64 v[130:131], v[42:43], 0, s[2:3]
	global_load_dword v108, v[130:131], off
	s_mov_b64 s[2:3], 0x2a000
	v_lshl_add_u64 v[130:131], v[42:43], 0, s[2:3]
	global_load_dword v109, v[130:131], off
	s_mov_b64 s[2:3], 0x2d000
	v_lshl_add_u64 v[130:131], v[42:43], 0, s[2:3]
	global_load_dword v110, v[130:131], off
	s_mov_b64 s[2:3], 0x30000
	v_lshl_add_u64 v[130:131], v[42:43], 0, s[2:3]
	global_load_dword v111, v[130:131], off

; DI void phase_prep(const Params& P, char* smem) {
;     ...
;       for (int k = 0; k < 128; ++k) {
;         const float wv = wp[(size_t)k * 3072];
; #pragma unroll
;         for (int r = 0; r < 17; ++r) acc[r] += s[r * 1024 + ks * 128 + k] * wv;
;       }
.Lprep4_w2:
	v_mov_b32_e32 v120, v112
	v_mov_b32_e32 v122, v113
	v_mov_b32_e32 v124, v114
	v_mov_b32_e32 v126, v115
	s_cmp_lt_u32 s1, 0x1c0
	s_cbranch_scc0 .Lprep4_n2
	s_mov_b64 s[2:3], 0x27000
	v_lshl_add_u64 v[130:131], v[42:43], 0, s[2:3]
	global_load_dword v112, v[130:131], off
	s_mov_b64 s[2:3], 0x2a000
	v_lshl_add_u64 v[130:131], v[42:43], 0, s[2:3]
	global_load_dword v113, v[130:131], off
	s_mov_b64 s[2:3], 0x2d000
	v_lshl_add_u64 v[130:131], v[42:43], 0, s[2:3]
	global_load_dword v114, v[130:131], off
	s_mov_b64 s[2:3], 0x30000
	v_lshl_add_u64 v[130:131], v[42:43], 0, s[2:3]
	global_load_dword v115, v[130:131], off

; DI void phase_prep(const Params& P, char* smem) {
;     ...
;       for (int k = 0; k < 128; ++k) {
;         const float wv = wp[(size_t)k * 3072];
; #pragma unroll
;         for (int r = 0; r < 17; ++r) acc[r] += s[r * 1024 + ks * 128 + k] * wv;
;       }
.Lprep4_w3:
	v_mov_b32_e32 v120, v116
	v_mov_b32_e32 v122, v117
	v_mov_b32_e32 v124, v118
	v_mov_b32_e32 v126, v119
	s_cmp_lt_u32 s1, 0x1c0
	s_cbranch_scc0 .Lprep4_n3
	s_mov_b64 s[2:3], 0x27000
	v_lshl_add_u64 v[130:131], v[42:43], 0, s[2:3]
	global_load_dword v116, v[130:131], off
	s_mov_b64 s[2:3], 0x2a000
	v_lshl_add_u64 v[130:131], v[42:43], 0, s[2:3]
	global_load_dword v117, v[130:131], off
	s_mov_b64 s[2:3], 0x2d000
	v_lshl_add_u64 v[130:131], v[42:43], 0, s[2:3]
	global_load_dword v118, v[130:131], off
	s_mov_b64 s[2:3], 0x30000
	v_lshl_add_u64 v[130:131], v[42:43], 0, s[2:3]
	global_load_dword v119, v[130:131], off
; DI void phase_prep(const Params& P, char* smem) {
;     ...
;       for (int k = 0; k < 128; ++k) {
;         const float wv = wp[(size_t)k * 3072];
; #pragma unroll
;         for (int r = 0; r < 17; ++r) acc[r] += s[r * 1024 + ks * 128 + k] * wv;
;       }
; #pragma unroll
;       for (int r = 0; r < 17; ++r) red[(ks * 17 + r) * 64 + nl] = acc[r];
;       __syncthreads();
;       for (int o = tid; o < 17 * 64; o += 512) {
;         const int r = o >> 6, n = o & 63;
;         float v = P.b_mod[layer * 3072 + n0 + n];
; #pragma unroll
;         for (int k2 = 0; k2 < 8; ++k2) v += red[(k2 * 17 + r) * 64 + n];
;         mods[(layer * 17 + r) * 3072 + n0 + n] = v;
.Lprep4_n3:
	v_add_u32_e32 v87, s1, v81
	ds_read_b128 v[20:23], v87
	ds_read_b128 v[0:3], v87 offset:4096
	ds_read_b128 v[24:27], v87 offset:8192
	ds_read_b128 v[4:7], v87 offset:12288
	ds_read_b128 v[28:31], v87 offset:16384
	ds_read_b128 v[8:11], v87 offset:20480
	ds_read_b128 v[32:35], v87 offset:24576
	ds_read_b128 v[12:15], v87 offset:28672
	ds_read_b128 v[44:47], v87 offset:32768
	ds_read_b128 v[16:19], v87 offset:36864
	s_waitcnt lgkmcnt(9)
	v_mov_b32_e32 v62, v20
	s_waitcnt lgkmcnt(8)
	v_mov_b32_e32 v63, v0
	s_waitcnt lgkmcnt(7)
	v_mov_b32_e32 v88, v24
	s_waitcnt lgkmcnt(6)
	v_mov_b32_e32 v89, v4
	v_mov_b32_e32 v0, v21
	v_mov_b32_e32 v52, v22
	v_mov_b32_e32 v53, v2
	v_mov_b32_e32 v2, v23
	v_mov_b32_e32 v4, v25
	v_mov_b32_e32 v54, v26
	v_mov_b32_e32 v55, v6
	v_mov_b32_e32 v6, v27
	ds_read_b128 v[24:27], v87 offset:40960
	ds_read_b128 v[20:23], v87 offset:45056
	s_waitcnt lgkmcnt(7)
	v_mov_b32_e32 v90, v28
	s_waitcnt lgkmcnt(6)
	v_mov_b32_e32 v91, v8
	v_mov_b32_e32 v8, v29
	v_mov_b32_e32 v56, v30
	v_mov_b32_e32 v57, v10
	v_mov_b32_e32 v10, v31
	s_waitcnt lgkmcnt(3)
	v_mov_b32_e32 v94, v44
	s_waitcnt lgkmcnt(2)
	v_mov_b32_e32 v95, v16
	v_mov_b32_e32 v16, v45
	v_mov_b32_e32 v44, v46
	v_mov_b32_e32 v45, v18
	v_mov_b32_e32 v18, v47
	s_waitcnt lgkmcnt(1)
	v_mov_b32_e32 v96, v24
	s_waitcnt lgkmcnt(0)
	v_mov_b32_e32 v97, v20
	v_mov_b32_e32 v20, v25
	v_mov_b32_e32 v46, v26
	v_mov_b32_e32 v47, v22
	v_mov_b32_e32 v22, v27
	ds_read_b128 v[28:31], v87 offset:49152
	ds_read_b128 v[24:27], v87 offset:53248
	v_mov_b32_e32 v92, v32
	v_mov_b32_e32 v93, v12
	v_mov_b32_e32 v12, v33
	v_mov_b32_e32 v58, v34
	v_mov_b32_e32 v59, v14
	v_mov_b32_e32 v14, v35
	s_waitcnt lgkmcnt(1)
	v_mov_b32_e32 v98, v28
	s_waitcnt lgkmcnt(0)
	v_mov_b32_e32 v99, v24
	v_mov_b32_e32 v24, v29
	v_mov_b32_e32 v48, v30
	v_mov_b32_e32 v49, v26
	v_mov_b32_e32 v26, v31
	ds_read_b128 v[32:35], v87 offset:57344
	ds_read_b128 v[28:31], v87 offset:61440
	s_mov_b32 s2, 0xffff7000
	s_add_i32 s1, s1, 16
	s_cmpk_eq_i32 s1, 0x200
	s_waitcnt lgkmcnt(1)
	v_mov_b32_e32 v100, v32
	v_add_co_u32_e32 v32, vcc, s2, v42
	s_waitcnt lgkmcnt(0)
	v_mov_b32_e32 v101, v28
	v_mov_b32_e32 v28, v33
	v_addc_co_u32_e32 v33, vcc, -1, v43, vcc
	v_mov_b32_e32 v102, v120
	v_add_u32_e32 v32, 0x10000, v87
	v_mov_b32_e32 v50, v34
	v_mov_b32_e32 v51, v30
	v_mov_b32_e32 v30, v35
	ds_read_b128 v[32:35], v32
	s_movk_i32 s2, 0xa000
	v_pk_fma_f32 v[62:63], v[102:103], v[62:63], v[60:61] op_sel_hi:[0,1,1]
	v_add_co_u32_e32 v60, vcc, s2, v42
	s_movk_i32 s2, 0xd000
	s_nop 0
	v_addc_co_u32_e32 v61, vcc, -1, v43, vcc
	v_pk_fma_f32 v[64:65], v[102:103], v[88:89], v[64:65] op_sel_hi:[0,1,1]
	v_add_co_u32_e32 v88, vcc, s2, v42
	v_pk_fma_f32 v[66:67], v[102:103], v[90:91], v[66:67] op_sel_hi:[0,1,1]
	s_waitcnt lgkmcnt(0)
	v_fmac_f32_e32 v86, v102, v32
	v_addc_co_u32_e32 v89, vcc, -1, v43, vcc
	v_mov_b32_e32 v90, v122
	s_nop 0
	v_mov_b32_e32 v60, v124
	v_mov_b32_e32 v32, v126
	v_pk_fma_f32 v[68:69], v[102:103], v[92:93], v[68:69] op_sel_hi:[0,1,1]
	v_pk_fma_f32 v[70:71], v[102:103], v[94:95], v[70:71] op_sel_hi:[0,1,1]
	v_pk_fma_f32 v[72:73], v[102:103], v[96:97], v[72:73] op_sel_hi:[0,1,1]
	v_pk_fma_f32 v[74:75], v[102:103], v[98:99], v[74:75] op_sel_hi:[0,1,1]
	v_pk_fma_f32 v[76:77], v[102:103], v[100:101], v[76:77] op_sel_hi:[0,1,1]
	s_mov_b64 s[2:3], 0xc000
	v_lshl_add_u64 v[42:43], v[42:43], 0, s[2:3]
	v_pk_fma_f32 v[62:63], v[90:91], v[0:1], v[62:63] op_sel_hi:[0,1,1]
	v_pk_fma_f32 v[64:65], v[90:91], v[4:5], v[64:65] op_sel_hi:[0,1,1]
	v_pk_fma_f32 v[66:67], v[90:91], v[8:9], v[66:67] op_sel_hi:[0,1,1]
	v_pk_fma_f32 v[68:69], v[90:91], v[12:13], v[68:69] op_sel_hi:[0,1,1]
	v_pk_fma_f32 v[0:1], v[90:91], v[16:17], v[70:71] op_sel_hi:[0,1,1]
	v_pk_fma_f32 v[4:5], v[90:91], v[20:21], v[72:73] op_sel_hi:[0,1,1]
	v_pk_fma_f32 v[8:9], v[90:91], v[24:25], v[74:75] op_sel_hi:[0,1,1]
	v_pk_fma_f32 v[12:13], v[90:91], v[28:29], v[76:77] op_sel_hi:[0,1,1]
	v_fmac_f32_e32 v86, v90, v33
	v_pk_fma_f32 v[16:17], v[60:61], v[52:53], v[62:63] op_sel_hi:[0,1,1]
	v_pk_fma_f32 v[20:21], v[60:61], v[54:55], v[64:65] op_sel_hi:[0,1,1]
	v_pk_fma_f32 v[24:25], v[60:61], v[56:57], v[66:67] op_sel_hi:[0,1,1]
	v_pk_fma_f32 v[28:29], v[60:61], v[58:59], v[68:69] op_sel_hi:[0,1,1]
	v_pk_fma_f32 v[0:1], v[60:61], v[44:45], v[0:1] op_sel_hi:[0,1,1]
	v_pk_fma_f32 v[4:5], v[60:61], v[46:47], v[4:5] op_sel_hi:[0,1,1]
	v_pk_fma_f32 v[8:9], v[60:61], v[48:49], v[8:9] op_sel_hi:[0,1,1]
	v_pk_fma_f32 v[12:13], v[60:61], v[50:51], v[12:13] op_sel_hi:[0,1,1]
	v_fmac_f32_e32 v86, v60, v34
	v_pk_fma_f32 v[60:61], v[32:33], v[2:3], v[16:17] op_sel_hi:[0,1,1]
	v_pk_fma_f32 v[64:65], v[32:33], v[6:7], v[20:21] op_sel_hi:[0,1,1]
	v_pk_fma_f32 v[66:67], v[32:33], v[10:11], v[24:25] op_sel_hi:[0,1,1]
	v_pk_fma_f32 v[68:69], v[32:33], v[14:15], v[28:29] op_sel_hi:[0,1,1]
	v_pk_fma_f32 v[70:71], v[32:33], v[18:19], v[0:1] op_sel_hi:[0,1,1]
	v_pk_fma_f32 v[72:73], v[32:33], v[22:23], v[4:5] op_sel_hi:[0,1,1]
	v_pk_fma_f32 v[74:75], v[32:33], v[26:27], v[8:9] op_sel_hi:[0,1,1]
	v_pk_fma_f32 v[76:77], v[32:33], v[30:31], v[12:13] op_sel_hi:[0,1,1]
	v_fmac_f32_e32 v86, v32, v35
	s_cbranch_scc0 .LBB0_840
	ds_write2st64_b32 v37, v60, v61 offset1:1
	ds_write2st64_b32 v37, v64, v65 offset0:2 offset1:3
	ds_write2st64_b32 v37, v66, v67 offset0:4 offset1:5
	ds_write2st64_b32 v37, v68, v69 offset0:6 offset1:7
	ds_write2st64_b32 v37, v70, v71 offset0:8 offset1:9
	ds_write2st64_b32 v37, v72, v73 offset0:10 offset1:11
	ds_write2st64_b32 v37, v74, v75 offset0:12 offset1:13
	ds_write2st64_b32 v37, v76, v77 offset0:14 offset1:15
	ds_write_b32 v37, v86 offset:4096
	s_waitcnt lgkmcnt(0)
	s_barrier
	s_and_saveexec_b64 s[2:3], s[42:43]
	v_readlane_b32 s50, v253, 61
	v_readlane_b32 s51, v253, 62
	s_cbranch_execz .LBB0_825
	s_mul_i32 s1, s44, 0xc00
	s_add_i32 s1, s1, s0
	v_or_b32_e32 v0, s1, v80
	v_readlane_b32 s4, v255, 4
	v_ashrrev_i32_e32 v1, 31, v0
	v_readlane_b32 s5, v255, 5
	v_readlane_b32 s6, v255, 6
	v_readlane_b32 s8, v255, 8
	v_readlane_b32 s9, v255, 9
	v_readlane_b32 s16, v255, 16
	v_readlane_b32 s17, v255, 17
	v_readlane_b32 s18, v255, 18
	v_readlane_b32 s19, v255, 19
	s_mul_i32 s44, s44, 17
	s_mov_b64 s[8:9], 0x800
	s_movk_i32 s6, 0x204
	s_brev_b32 s5, 1
	s_movk_i32 s19, 0xff
	s_movk_i32 s18, 0x1f8
	v_lshl_add_u64 v[0:1], v[0:1], 2, s[16:17]
	v_readlane_b32 s17, v255, 35
	s_mov_b32 s16, 0x1ffffe0
	v_or_b32_e32 v2, s0, v80
	s_mov_b64 s[0:1], 0
	v_mov_b32_e32 v3, v36
	v_readlane_b32 s7, v255, 7
	v_readlane_b32 s10, v255, 10
	v_readlane_b32 s11, v255, 11
	v_readlane_b32 s12, v255, 12
	v_readlane_b32 s13, v255, 13
	v_readlane_b32 s14, v255, 14
	v_readlane_b32 s15, v255, 15
